# v29 + GLA prep gate loop: removed the denormal pre-scaling and infinity select around v_log_f32 (argument 1+e is in [1,2]; compensated ln2 multiply kept, bit-identical)
# baseline (speedup 1.0000x reference)
; LPHASE void phase_gla_prep(char* ws_, const float* x_, float* out_, const float* meta_, int nseq_, char* lds) {
;     ...
;       for (int ii = 0; ii < 16; ++ii) { const int i = ig * 16 + ii; float sf = bfv, sb = bbv; const float* a = af + i * 32;
; #pragma unroll
;         for (int k = 0; k < 16; ++k) { sf += a[k] * wf[k]; sb += a[16 + k] * wb[k]; }
;         float lf = (fminf(sf, 0.f) - __logf(1.f + __expf(-fabsf(sf)))) * (1.f / 16.f), lb = (fminf(sb, 0.f) - __logf(1.f + __expf(-fabsf(sb)))) * (1.f / 16.f);
;         if (ismeta && i >= 16) { lf = 0.f; lb = 0.f; }
;         lgF[i * LGP + d] = lf; lgB[i * LGP + d] = lb; tfl += lf; tbl += lb; }
.LBB0_506:
	v_add_u32_e32 v85, s12, v80
	v_add_u32_e32 v96, 0x10200, v85
	ds_read_b128 v[100:103], v96
	ds_read_b128 v[104:107], v96 offset:64
	ds_read_b128 v[108:111], v96 offset:16
	ds_read_b128 v[112:115], v96 offset:80
	ds_read_b128 v[116:119], v96 offset:32
	ds_read_b128 v[120:123], v96 offset:96
	ds_read_b128 v[124:127], v96 offset:48
	ds_read_b128 v[128:131], v96 offset:112
	ds_read_b128 v[136:139], v96 offset:128
	ds_read_b128 v[140:143], v96 offset:192
	ds_read_b128 v[144:147], v96 offset:144
	ds_read_b128 v[148:151], v96 offset:208
	ds_read_b128 v[152:155], v96 offset:160
	ds_read_b128 v[156:159], v96 offset:224
	ds_read_b128 v[160:163], v96 offset:176
	ds_read_b128 v[164:167], v96 offset:240
	s_waitcnt vmcnt(0) lgkmcnt(0)
	s_addk_i32 s12, 0x100
	v_fma_f32 v94, v74, v100, v78
	v_fmac_f32_e32 v94, v77, v101
	v_fmac_f32_e32 v94, v62, v102
	v_fmac_f32_e32 v94, v70, v103
	v_fma_f32 v95, v75, v104, v79
	v_fmac_f32_e32 v95, v76, v105
	v_fmac_f32_e32 v95, v63, v106
	v_fmac_f32_e32 v95, v71, v107
	v_fmac_f32_e32 v94, v64, v108
	v_fmac_f32_e32 v94, v68, v109
	v_fmac_f32_e32 v94, v67, v110
	v_fmac_f32_e32 v94, v72, v111
	v_fmac_f32_e32 v95, v65, v112
	v_fmac_f32_e32 v95, v66, v113
	v_fmac_f32_e32 v95, v69, v114
	v_fmac_f32_e32 v95, v73, v115
	v_pk_mul_f32 v[86:87], v[4:5], v[116:117]
	s_nop 0
	v_add_f32_e32 v86, v94, v86
	v_add_f32_e32 v94, v86, v87
	v_pk_mul_f32 v[86:87], v[6:7], v[120:121]
	s_nop 0
	v_add_f32_e32 v86, v95, v86
	v_add_f32_e32 v90, v86, v87
	v_pk_mul_f32 v[86:87], v[8:9], v[118:119]
	s_nop 0
	v_add_f32_e32 v86, v94, v86
	v_add_f32_e32 v91, v86, v87
	v_pk_mul_f32 v[86:87], v[10:11], v[122:123]
	s_nop 0
	v_add_f32_e32 v86, v90, v86
	v_add_f32_e32 v94, v86, v87
	v_pk_mul_f32 v[86:87], v[12:13], v[124:125]
	s_nop 0
	v_add_f32_e32 v86, v91, v86
	v_add_f32_e32 v95, v86, v87
	v_pk_mul_f32 v[86:87], v[14:15], v[128:129]
	s_nop 0
	v_add_f32_e32 v86, v94, v86
	v_add_f32_e32 v90, v86, v87
	v_pk_mul_f32 v[86:87], v[22:23], v[126:127]
	s_nop 0
	v_add_f32_e32 v86, v95, v86
	v_add_f32_e32 v88, v86, v87
	v_pk_mul_f32 v[86:87], v[24:25], v[130:131]
	s_nop 0
	v_add_f32_e32 v86, v90, v86
	v_add_f32_e32 v86, v86, v87
	v_min_f32_e32 v87, 0, v88
	v_mul_f32_e64 v88, |v88|, s6
	v_exp_f32_e32 v88, v88
	s_nop 0
	v_add_f32_e32 v88, 1.0, v88
	v_log_f32_e32 v88, v88
	s_nop 0
	v_mul_f32_e32 v89, 0x3f317217, v88
	v_fma_f32 v89, v88, s13, -v89
	v_fmac_f32_e32 v89, 0x3377d1cf, v88
	v_fmac_f32_e32 v89, 0x3f317217, v88
	v_mov_b32_e32 v88, v89
	v_sub_f32_e32 v87, v87, v88
	v_min_f32_e32 v88, 0, v86
	v_mul_f32_e64 v86, |v86|, s6
	v_exp_f32_e32 v86, v86
	v_mul_f32_e32 v87, 0x3d800000, v87
	v_add_f32_e32 v86, 1.0, v86
	v_log_f32_e32 v86, v86
	s_nop 0
	v_mul_f32_e32 v89, 0x3f317217, v86
	v_fma_f32 v89, v86, s13, -v89
	v_fmac_f32_e32 v89, 0x3377d1cf, v86
	v_fmac_f32_e32 v89, 0x3f317217, v86
	v_mov_b32_e32 v86, v89
	v_sub_f32_e32 v86, v88, v86
	v_cmp_lt_i32_e32 vcc, 15, v82
	v_mul_f32_e32 v86, 0x3d800000, v86
	s_and_b64 s[0:1], s[26:27], vcc
	v_cndmask_b32_e64 v86, v86, 0, s[0:1]
	v_cndmask_b32_e64 v87, v87, 0, s[0:1]
	ds_write_b32 v81, v87
	ds_write_b32 v81, v86 offset:33024
	v_add_f32_e32 v84, v84, v86
	v_add_f32_e32 v83, v83, v87
	v_fma_f32 v94, v74, v136, v78
	v_fmac_f32_e32 v94, v77, v137
	v_fmac_f32_e32 v94, v62, v138
	v_fmac_f32_e32 v94, v70, v139
	v_fma_f32 v95, v75, v140, v79
	v_fmac_f32_e32 v95, v76, v141
	v_fmac_f32_e32 v95, v63, v142
	v_fmac_f32_e32 v95, v71, v143
	v_fmac_f32_e32 v94, v64, v144
	v_fmac_f32_e32 v94, v68, v145
	v_fmac_f32_e32 v94, v67, v146
	v_fmac_f32_e32 v94, v72, v147
	v_fmac_f32_e32 v95, v65, v148
	v_fmac_f32_e32 v95, v66, v149
	v_fmac_f32_e32 v95, v69, v150
	v_fmac_f32_e32 v95, v73, v151
	v_pk_mul_f32 v[86:87], v[4:5], v[152:153]
	s_nop 0
	v_add_f32_e32 v86, v94, v86
	v_add_f32_e32 v94, v86, v87
	v_pk_mul_f32 v[86:87], v[6:7], v[156:157]
	s_nop 0
	v_add_f32_e32 v86, v95, v86
	v_add_f32_e32 v90, v86, v87
	v_pk_mul_f32 v[86:87], v[8:9], v[154:155]
	s_nop 0
	v_add_f32_e32 v86, v94, v86
	v_add_f32_e32 v91, v86, v87
	v_pk_mul_f32 v[86:87], v[10:11], v[158:159]
	s_nop 0
	v_add_f32_e32 v86, v90, v86
	v_add_f32_e32 v94, v86, v87
	v_pk_mul_f32 v[86:87], v[12:13], v[160:161]
	s_nop 0
	v_add_f32_e32 v86, v91, v86
	v_add_f32_e32 v95, v86, v87
	v_pk_mul_f32 v[86:87], v[14:15], v[164:165]
	s_nop 0
	v_add_f32_e32 v85, v94, v86
	v_add_f32_e32 v85, v85, v87
	v_pk_mul_f32 v[86:87], v[22:23], v[162:163]
	s_nop 0
	v_add_f32_e32 v86, v95, v86
	v_add_f32_e32 v88, v86, v87
	v_pk_mul_f32 v[86:87], v[24:25], v[166:167]
	s_nop 0
	v_add_f32_e32 v85, v85, v86
	v_add_f32_e32 v85, v85, v87
	v_mul_f32_e64 v87, |v88|, s6
	v_exp_f32_e32 v87, v87
	v_min_f32_e32 v86, 0, v88
	v_add_f32_e32 v87, 1.0, v87
	v_log_f32_e32 v87, v87
	s_nop 0
	v_mul_f32_e32 v88, 0x3f317217, v87
	v_fma_f32 v88, v87, s13, -v88
	v_fmac_f32_e32 v88, 0x3377d1cf, v87
	v_fmac_f32_e32 v88, 0x3f317217, v87
	v_mov_b32_e32 v87, v88
	v_sub_f32_e32 v86, v86, v87
	v_min_f32_e32 v87, 0, v85
	v_mul_f32_e64 v85, |v85|, s6
	v_exp_f32_e32 v85, v85
	v_mul_f32_e32 v86, 0x3d800000, v86
	v_add_f32_e32 v85, 1.0, v85
	v_log_f32_e32 v85, v85
	s_nop 0
	v_mul_f32_e32 v88, 0x3f317217, v85
	v_fma_f32 v88, v85, s13, -v88
	v_fmac_f32_e32 v88, 0x3377d1cf, v85
	v_fmac_f32_e32 v88, 0x3f317217, v85
	v_mov_b32_e32 v85, v88
	v_sub_f32_e32 v85, v87, v85
	v_cmp_lt_i32_e32 vcc, 14, v82
	v_mul_f32_e32 v85, 0x3d800000, v85
	s_and_b64 s[0:1], s[26:27], vcc
	v_cndmask_b32_e64 v85, v85, 0, s[0:1]
	v_cndmask_b32_e64 v86, v86, 0, s[0:1]
	ds_write_b32 v81, v86 offset:516
	ds_write_b32 v81, v85 offset:33540
	v_add_f32_e32 v83, v83, v86
	v_add_f32_e32 v84, v84, v85
	v_add_u32_e32 v82, 2, v82
	v_add_u32_e32 v81, 0x408, v81
	s_cmpk_eq_i32 s12, 0x800
	s_cbranch_scc0 .LBB0_506
	v_and_b32_e32 v4, 0x3fffff80, v16
	v_lshl_add_u32 v6, v2, 2, s85
	v_lshl_add_u32 v5, v16, 2, s85
	v_lshl_add_u32 v4, v4, 2, v6
	ds_write_b32 v5, v83
	ds_write_b32 v4, v84 offset:2048
	s_waitcnt lgkmcnt(0)
	s_barrier
	ds_read2st64_b32 v[10:11], v6 offset1:2
	ds_read2st64_b32 v[8:9], v6 offset0:4 offset1:6
	ds_read2st64_b32 v[4:5], v6 offset0:8 offset1:10
	ds_read2st64_b32 v[6:7], v6 offset0:12 offset1:14
	s_movk_i32 s0, 0x80
	v_cmp_gt_u32_e32 vcc, s0, v16
	s_movk_i32 s0, 0x7f
	s_waitcnt lgkmcnt(3)
	v_add_f32_e32 v11, v10, v11
	v_cmp_lt_u32_e64 s[0:1], s0, v16
	v_mov_b32_e32 v13, 0
	s_and_saveexec_b64 s[26:27], s[0:1]
	s_cbranch_execz .LBB0_513
	v_cmp_lt_i32_e64 s[0:1], 1, v49
	s_mov_b64 s[28:29], 0
	s_and_saveexec_b64 s[30:31], s[0:1]
	s_xor_b64 s[42:43], exec, s[30:31]
	s_cbranch_execnz .LBB0_527
	s_or_saveexec_b64 s[42:43], s[42:43]
	v_mov_b32_e32 v13, v11
	s_xor_b64 exec, exec, s[42:43]
	s_cbranch_execnz .LBB0_530
